# stack5 + rescale test moved off the step top (fallback to plain P.V + original rescale code), first V fragments read during QK^T chain with counted lgkmcnt
# speedup vs baseline: 1.0296x; 1.0066x over previous
.Li0_entry:
	v_add_u32_e32 v167, s79, v147
	v_add_u32_e32 v227, s79, v149
	v_add_u32_e32 v194, s79, v151
	v_add_u32_e32 v195, s79, v153
	ds_read_b128 v[64:67], v167
	ds_read_b128 v[188:191], v227
	ds_read_b128 v[228:231], v194
	s_waitcnt lgkmcnt(2)
	v_mfma_f32_32x32x16_bf16 v[64:79], v[64:67], v[80:83], 0
	s_waitcnt lgkmcnt(1)
	v_mfma_f32_32x32x16_bf16 v[64:79], v[188:191], v[84:87], v[64:79]
	ds_read_b128 v[188:191], v195
	s_mov_b64 s[54:55], 0xe404000
	s_add_i32 m0, s96, 0x8000
	v_lshl_add_u64 v[192:193], v[134:135], 0, s[54:55]
	s_nop 0
	global_load_lds_dwordx4 v[192:193], off
	v_cndmask_b32_e64 v173, v113, v121, s[2:3]
	v_cndmask_b32_e64 v172, v112, v120, s[2:3]
	v_cndmask_b32_e64 v177, v121, v113, s[2:3]
	v_cndmask_b32_e64 v176, v120, v112, s[2:3]
	s_waitcnt lgkmcnt(1)
	v_mfma_f32_32x32x16_bf16 v[64:79], v[228:231], v[88:91], v[64:79]
	ds_read_b128 v[228:231], v167 offset:128
	s_mov_b64 s[54:55], 0xe406000
	s_add_i32 m0, s96, 0xa000
	v_lshl_add_u64 v[192:193], v[134:135], 0, s[54:55]
	s_nop 0
	global_load_lds_dwordx4 v[192:193], off
	v_cndmask_b32_e64 v171, v119, v127, s[2:3]
	v_cndmask_b32_e64 v170, v118, v126, s[2:3]
	v_cndmask_b32_e64 v169, v117, v125, s[2:3]
	v_cndmask_b32_e64 v168, v116, v124, s[2:3]
	s_waitcnt lgkmcnt(1)
	v_mfma_f32_32x32x16_bf16 v[64:79], v[188:191], v[92:95], v[64:79]
	ds_read_b128 v[188:191], v227 offset:128
	s_mov_b64 s[54:55], 0xe804000
	s_add_i32 m0, s96, 0xc000
	v_lshl_add_u64 v[192:193], v[134:135], 0, s[54:55]
	s_nop 0
	global_load_lds_dwordx4 v[192:193], off
	v_cndmask_b32_e64 v175, v115, v123, s[2:3]
	v_cndmask_b32_e64 v174, v114, v122, s[2:3]
	v_cndmask_b32_e64 v127, v127, v119, s[2:3]
	v_cndmask_b32_e64 v126, v126, v118, s[2:3]
	s_waitcnt lgkmcnt(1)
	v_mfma_f32_32x32x16_bf16 v[64:79], v[228:231], v[96:99], v[64:79]
	ds_read_b128 v[228:231], v194 offset:128
	s_mov_b64 s[54:55], 0xe806000
	s_add_i32 m0, s96, 0xe000
	v_lshl_add_u64 v[192:193], v[134:135], 0, s[54:55]
	s_nop 0
	global_load_lds_dwordx4 v[192:193], off
	v_cndmask_b32_e64 v125, v125, v117, s[2:3]
	v_cndmask_b32_e64 v124, v124, v116, s[2:3]
	v_cndmask_b32_e64 v179, v123, v115, s[2:3]
	v_cndmask_b32_e64 v178, v122, v114, s[2:3]
	s_waitcnt lgkmcnt(1)
	v_mfma_f32_32x32x16_bf16 v[64:79], v[188:191], v[100:103], v[64:79]
	ds_read_b128 v[188:191], v195 offset:128
	s_cmp_gt_i32 s19, s18
	s_cbranch_scc1 .Li0_kskip
	v_lshl_add_u64 v[192:193], s[50:51], 0, v[130:131]
	s_mov_b64 s[54:55], 0xc408000
	s_mov_b32 m0, s97
	v_lshl_add_u64 v[192:193], v[192:193], 0, s[54:55]
	s_nop 0
	global_load_lds_dwordx4 v[192:193], off
	v_lshl_add_u64 v[192:193], s[50:51], 0, v[130:131]
	s_mov_b64 s[54:55], 0xc40a000
	s_mov_b32 m0, s26
	v_lshl_add_u64 v[192:193], v[192:193], 0, s[54:55]
	s_nop 0
	global_load_lds_dwordx4 v[192:193], off
.Li0_kskip:
	ds_read_b64_tr_b16 v[180:181], v158 offset:0
	ds_read_b64_tr_b16 v[182:183], v158 offset:0x800
	ds_read_b64_tr_b16 v[184:185], v158 offset:0x1000
	ds_read_b64_tr_b16 v[186:187], v158 offset:0x1800
	s_waitcnt lgkmcnt(5)
	v_mfma_f32_32x32x16_bf16 v[64:79], v[228:231], v[104:107], v[64:79]
	v_max_f32_e32 v194, v166, v166
	v_max_f32_e32 v195, v164, v164
	v_max_f32_e32 v194, v195, v194
	v_sub_f32_e32 v195, v194, v165
	v_mul_f32_e32 v195, 0x3db504f3, v195
	v_cmp_ge_f32_e32 vcc, s88, v195
	s_waitcnt lgkmcnt(4)
	v_mfma_f32_32x32x16_bf16 v[64:79], v[188:191], v[108:111], v[64:79]
	s_cmp_eq_u64 vcc, exec
	s_cbranch_scc0 .Li0_fb
	v_mov_b32_e32 v166, v165
	s_sub_i32 s52, s83, 64
	s_cmp_le_i32 s52, s25
	s_cbranch_scc1 .Li0_sm
	s_nop 7
	v_add_u32_e32 v112, 0x5b, v162
	v_cmp_gt_u32_e32 vcc, s86, v112
	v_add_u32_e32 v112, s83, v163
	v_add_u32_e32 v112, 0xffffffa1, v112
	v_cndmask_b32_e32 v64, v141, v64, vcc
	v_cmp_lt_u32_e32 vcc, s87, v112
	v_add_u32_e32 v112, 0x59, v162
	s_nop 0
	v_cndmask_b32_e32 v65, v141, v65, vcc
	v_cmp_gt_u32_e32 vcc, s86, v112
	v_add_u32_e32 v112, 0x58, v162
	s_nop 0
	v_cndmask_b32_e32 v66, v141, v66, vcc
	v_cmp_gt_u32_e32 vcc, s86, v112
	v_add_u32_e32 v112, 0x53, v162
	s_nop 0
	v_cndmask_b32_e32 v67, v141, v67, vcc
	v_cmp_gt_u32_e32 vcc, s86, v112
	v_add_u32_e32 v112, 0x52, v162
	s_nop 0
	v_cndmask_b32_e32 v68, v141, v68, vcc
	v_cmp_gt_u32_e32 vcc, s86, v112
	v_add_u32_e32 v112, 0x51, v162
	s_nop 0
	v_cndmask_b32_e32 v69, v141, v69, vcc
	v_cmp_gt_u32_e32 vcc, s86, v112
	v_add_u32_e32 v112, 0x50, v162
	s_nop 0
	v_cndmask_b32_e32 v70, v141, v70, vcc
	v_cmp_gt_u32_e32 vcc, s86, v112
	v_add_u32_e32 v112, 0x4b, v162
	s_nop 0
	v_cndmask_b32_e32 v71, v141, v71, vcc
	v_cmp_gt_u32_e32 vcc, s86, v112
	v_add_u32_e32 v112, 0x4a, v162
	s_nop 0
	v_cndmask_b32_e32 v72, v141, v72, vcc
	v_cmp_gt_u32_e32 vcc, s86, v112
	v_add_u32_e32 v112, 0x49, v162
	s_nop 0
	v_cndmask_b32_e32 v73, v141, v73, vcc
	v_cmp_gt_u32_e32 vcc, s86, v112
	v_add_u32_e32 v112, 0x48, v162
	s_nop 0
	v_cndmask_b32_e32 v74, v141, v74, vcc
	v_cmp_gt_u32_e32 vcc, s86, v112
	v_add_u32_e32 v112, 0x43, v162
	s_nop 0
	v_cndmask_b32_e32 v75, v141, v75, vcc
	v_cmp_gt_u32_e32 vcc, s86, v112
	v_add_u32_e32 v112, 0x42, v162
	s_nop 0
	v_cndmask_b32_e32 v76, v141, v76, vcc
	v_cmp_gt_u32_e32 vcc, s86, v112
	v_add_u32_e32 v112, 0x41, v162
	s_nop 0
	v_cndmask_b32_e32 v77, v141, v77, vcc
	v_cmp_gt_u32_e32 vcc, s86, v112
	v_add_u32_e32 v112, 64, v162
	s_nop 0
	v_cndmask_b32_e32 v78, v141, v78, vcc
	v_cmp_gt_u32_e32 vcc, s86, v112
	s_nop 1
	v_cndmask_b32_e32 v79, v141, v79, vcc
.Li0_sm:
	ds_read_b64_tr_b16 v[188:189], v158 offset:0x2000
	ds_read_b64_tr_b16 v[190:191], v158 offset:0x2800
	ds_read_b64_tr_b16 v[192:193], v158 offset:0x3000
	ds_read_b64_tr_b16 v[194:195], v158 offset:0x3800
	s_waitcnt lgkmcnt(4)
	s_nop 1
	v_mfma_f32_32x32x16_bf16 v[48:63], v[176:179], v[180:183], v[48:63]
	ds_read_b64_tr_b16 v[180:181], v158 offset:0x200
	ds_read_b64_tr_b16 v[182:183], v158 offset:0xa00
	v_mul_f32_e32 v114, 0xbe0293ee, v166
	v_max_f32_e32 v112, v65, v65
	v_max_f32_e32 v113, v64, v64
	v_fmamk_f32 v64, v64, 0x3e0293ee, v114
	v_max_f32_e32 v112, v113, v112
	v_exp_f32_e32 v64, v64
	v_mfma_f32_32x32x16_bf16 v[48:63], v[124:127], v[184:187], v[48:63]
	ds_read_b64_tr_b16 v[184:185], v158 offset:0x1200
	ds_read_b64_tr_b16 v[186:187], v158 offset:0x1a00
	v_fmamk_f32 v65, v65, 0x3e0293ee, v114
	v_max3_f32 v112, v112, v66, v67
	v_exp_f32_e32 v65, v65
	v_fmamk_f32 v66, v66, 0x3e0293ee, v114
	v_exp_f32_e32 v66, v66
	v_fmamk_f32 v67, v67, 0x3e0293ee, v114
	s_waitcnt lgkmcnt(6)
	v_mfma_f32_32x32x16_bf16 v[48:63], v[172:175], v[188:191], v[48:63]
	ds_read_b64_tr_b16 v[188:189], v158 offset:0x2200
	ds_read_b64_tr_b16 v[190:191], v158 offset:0x2a00
	v_max3_f32 v112, v112, v68, v69
	v_exp_f32_e32 v67, v67
	v_fmamk_f32 v68, v68, 0x3e0293ee, v114
	v_add_f32_e32 v115, 0, v64
	v_exp_f32_e32 v68, v68
	v_fmamk_f32 v69, v69, 0x3e0293ee, v114
	s_waitcnt lgkmcnt(6)
	v_mfma_f32_32x32x16_bf16 v[48:63], v[168:171], v[192:195], v[48:63]
	ds_read_b64_tr_b16 v[192:193], v158 offset:0x3200
	ds_read_b64_tr_b16 v[194:195], v158 offset:0x3a00
	v_max3_f32 v112, v112, v70, v71
	v_add_f32_e32 v115, v65, v115
	v_exp_f32_e32 v69, v69
	v_fmamk_f32 v70, v70, 0x3e0293ee, v114
	v_add_f32_e32 v115, v66, v115
	v_exp_f32_e32 v70, v70
	s_waitcnt lgkmcnt(0)
	v_mfma_f32_32x32x16_bf16 v[32:47], v[176:179], v[180:183], v[32:47]
	ds_read_b64_tr_b16 v[180:181], v158 offset:0x400
	ds_read_b64_tr_b16 v[182:183], v158 offset:0xc00
	v_fmamk_f32 v71, v71, 0x3e0293ee, v114
	v_max3_f32 v112, v112, v72, v73
	v_add_f32_e32 v115, v67, v115
	v_exp_f32_e32 v71, v71
	v_fmamk_f32 v72, v72, 0x3e0293ee, v114
	v_add_f32_e32 v115, v68, v115
	v_mfma_f32_32x32x16_bf16 v[32:47], v[124:127], v[184:187], v[32:47]
	ds_read_b64_tr_b16 v[184:185], v158 offset:0x1400
	ds_read_b64_tr_b16 v[186:187], v158 offset:0x1c00
	v_exp_f32_e32 v72, v72
	v_fmamk_f32 v73, v73, 0x3e0293ee, v114
	v_max3_f32 v112, v112, v74, v75
	v_add_f32_e32 v115, v69, v115
	v_exp_f32_e32 v73, v73
	v_fmamk_f32 v74, v74, 0x3e0293ee, v114
	v_mfma_f32_32x32x16_bf16 v[32:47], v[172:175], v[188:191], v[32:47]
	ds_read_b64_tr_b16 v[188:189], v158 offset:0x2400
	ds_read_b64_tr_b16 v[190:191], v158 offset:0x2c00
	v_add_f32_e32 v115, v70, v115
	v_exp_f32_e32 v74, v74
	v_fmamk_f32 v75, v75, 0x3e0293ee, v114
	v_max3_f32 v112, v112, v76, v77
	v_add_f32_e32 v115, v71, v115
	v_exp_f32_e32 v75, v75
	v_mfma_f32_32x32x16_bf16 v[32:47], v[168:171], v[192:195], v[32:47]
	ds_read_b64_tr_b16 v[192:193], v158 offset:0x3400
	ds_read_b64_tr_b16 v[194:195], v158 offset:0x3c00
	v_fmamk_f32 v76, v76, 0x3e0293ee, v114
	v_add_f32_e32 v115, v72, v115
	v_exp_f32_e32 v76, v76
	v_fmamk_f32 v77, v77, 0x3e0293ee, v114
	v_max3_f32 v112, v112, v78, v79
	v_add_f32_e32 v115, v73, v115
	s_waitcnt lgkmcnt(0)
	v_mfma_f32_32x32x16_bf16 v[16:31], v[176:179], v[180:183], v[16:31]
	ds_read_b64_tr_b16 v[180:181], v158 offset:0x600
	ds_read_b64_tr_b16 v[182:183], v158 offset:0xe00
	v_exp_f32_e32 v77, v77
	v_fmamk_f32 v78, v78, 0x3e0293ee, v114
	v_add_f32_e32 v115, v74, v115
	v_exp_f32_e32 v78, v78
	v_fmac_f32_e32 v114, 0x3e0293ee, v79
	v_add_f32_e32 v115, v75, v115
	v_mfma_f32_32x32x16_bf16 v[16:31], v[124:127], v[184:187], v[16:31]
	ds_read_b64_tr_b16 v[184:185], v158 offset:0x1600
	ds_read_b64_tr_b16 v[186:187], v158 offset:0x1e00
	v_exp_f32_e32 v79, v114
	v_add_f32_e32 v114, v76, v115
	v_mov_b32_e32 v113, v112
	v_add_f32_e32 v114, v77, v114
	s_nop 0
	v_permlane32_swap_b32_e32 v112, v113
	v_add_f32_e32 v114, v78, v114
	v_mfma_f32_32x32x16_bf16 v[16:31], v[172:175], v[188:191], v[16:31]
	ds_read_b64_tr_b16 v[188:189], v158 offset:0x2600
	ds_read_b64_tr_b16 v[190:191], v158 offset:0x2e00
	v_add_f32_e32 v120, v79, v114
	v_max_f32_e32 v113, v113, v113
	v_max_f32_e32 v112, v112, v112
	v_max_f32_e32 v164, v112, v113
	v_mov_b32_e32 v121, v120
	v_cvt_pk_bf16_f32 v112, v64, v65
	v_mfma_f32_32x32x16_bf16 v[16:31], v[168:171], v[192:195], v[16:31]
	ds_read_b64_tr_b16 v[192:193], v158 offset:0x3600
	ds_read_b64_tr_b16 v[194:195], v158 offset:0x3e00
	v_cvt_pk_bf16_f32 v113, v66, v67
	v_cvt_pk_bf16_f32 v114, v68, v69
	v_cvt_pk_bf16_f32 v115, v70, v71
	v_cvt_pk_bf16_f32 v116, v72, v73
	v_cvt_pk_bf16_f32 v117, v74, v75
	v_cvt_pk_bf16_f32 v118, v76, v77
	s_waitcnt lgkmcnt(0)
	v_mfma_f32_32x32x16_bf16 v[0:15], v[176:179], v[180:183], v[0:15]
	v_cvt_pk_bf16_f32 v119, v78, v79
	s_nop 1
	v_permlane32_swap_b32_e32 v120, v121
	v_permlane32_swap_b32_e32 v112, v114
	v_permlane32_swap_b32_e32 v113, v115
	v_permlane32_swap_b32_e32 v116, v118
	v_permlane32_swap_b32_e32 v117, v119
	v_mfma_f32_32x32x16_bf16 v[0:15], v[124:127], v[184:187], v[0:15]
	ds_write_b128 v157, v[112:115] offset:4096
	ds_write_b128 v157, v[116:119] offset:5120
	v_add_f32_e32 v120, v120, v121
	v_add_f32_e32 v155, v155, v120
	v_mfma_f32_32x32x16_bf16 v[0:15], v[172:175], v[188:191], v[0:15]
	v_mfma_f32_32x32x16_bf16 v[0:15], v[168:171], v[192:195], v[0:15]
	s_and_saveexec_b64 s[52:53], s[4:5]
	ds_write_b32 v160, v164 offset:8448
	s_or_b64 exec, exec, s[52:53]
	s_waitcnt vmcnt(0)
	s_waitcnt vmcnt(0) lgkmcnt(0)
	s_barrier
	s_branch .LBB0_748
.Li0_fb:
	ds_read_b64_tr_b16 v[180:181], v158 offset:0
	ds_read_b64_tr_b16 v[182:183], v158 offset:0x800
	ds_read_b64_tr_b16 v[184:185], v158 offset:0x1000
	ds_read_b64_tr_b16 v[186:187], v158 offset:0x1800
	ds_read_b64_tr_b16 v[188:189], v158 offset:0x2000
	ds_read_b64_tr_b16 v[190:191], v158 offset:0x2800
	ds_read_b64_tr_b16 v[192:193], v158 offset:0x3000
	ds_read_b64_tr_b16 v[194:195], v158 offset:0x3800
	s_waitcnt lgkmcnt(0)
	s_waitcnt lgkmcnt(0)
	v_max_f32_e32 v120, v166, v166
	v_max_f32_e32 v121, v164, v164
	v_max_f32_e32 v120, v121, v120
	s_nop 1
	v_mfma_f32_32x32x16_bf16 v[48:63], v[176:179], v[180:183], v[48:63]
	ds_read_b64_tr_b16 v[180:181], v158 offset:0x200
	ds_read_b64_tr_b16 v[182:183], v158 offset:0xa00
	v_mfma_f32_32x32x16_bf16 v[48:63], v[124:127], v[184:187], v[48:63]
	ds_read_b64_tr_b16 v[184:185], v158 offset:0x1200
	ds_read_b64_tr_b16 v[186:187], v158 offset:0x1a00
	v_mfma_f32_32x32x16_bf16 v[48:63], v[172:175], v[188:191], v[48:63]
	ds_read_b64_tr_b16 v[188:189], v158 offset:0x2200
	ds_read_b64_tr_b16 v[190:191], v158 offset:0x2a00
	v_mfma_f32_32x32x16_bf16 v[48:63], v[168:171], v[192:195], v[48:63]
	ds_read_b64_tr_b16 v[192:193], v158 offset:0x3200
	ds_read_b64_tr_b16 v[194:195], v158 offset:0x3a00
	s_waitcnt lgkmcnt(0)
	v_mfma_f32_32x32x16_bf16 v[32:47], v[176:179], v[180:183], v[32:47]
	ds_read_b64_tr_b16 v[180:181], v158 offset:0x400
	ds_read_b64_tr_b16 v[182:183], v158 offset:0xc00
	v_mfma_f32_32x32x16_bf16 v[32:47], v[124:127], v[184:187], v[32:47]
	ds_read_b64_tr_b16 v[184:185], v158 offset:0x1400
	ds_read_b64_tr_b16 v[186:187], v158 offset:0x1c00
	v_mfma_f32_32x32x16_bf16 v[32:47], v[172:175], v[188:191], v[32:47]
	ds_read_b64_tr_b16 v[188:189], v158 offset:0x2400
	ds_read_b64_tr_b16 v[190:191], v158 offset:0x2c00
	v_mfma_f32_32x32x16_bf16 v[32:47], v[168:171], v[192:195], v[32:47]
	ds_read_b64_tr_b16 v[192:193], v158 offset:0x3400
	ds_read_b64_tr_b16 v[194:195], v158 offset:0x3c00
	s_waitcnt lgkmcnt(0)
	v_mfma_f32_32x32x16_bf16 v[16:31], v[176:179], v[180:183], v[16:31]
	ds_read_b64_tr_b16 v[180:181], v158 offset:0x600
	ds_read_b64_tr_b16 v[182:183], v158 offset:0xe00
	v_mfma_f32_32x32x16_bf16 v[16:31], v[124:127], v[184:187], v[16:31]
	ds_read_b64_tr_b16 v[184:185], v158 offset:0x1600
	ds_read_b64_tr_b16 v[186:187], v158 offset:0x1e00
	v_mfma_f32_32x32x16_bf16 v[16:31], v[172:175], v[188:191], v[16:31]
	ds_read_b64_tr_b16 v[188:189], v158 offset:0x2600
	ds_read_b64_tr_b16 v[190:191], v158 offset:0x2e00
	v_mfma_f32_32x32x16_bf16 v[16:31], v[168:171], v[192:195], v[16:31]
	ds_read_b64_tr_b16 v[192:193], v158 offset:0x3600
	ds_read_b64_tr_b16 v[194:195], v158 offset:0x3e00
	s_waitcnt lgkmcnt(0)
	v_mfma_f32_32x32x16_bf16 v[0:15], v[176:179], v[180:183], v[0:15]
	v_sub_f32_e32 v121, v120, v165
	v_mul_f32_e32 v121, 0x3db504f3, v121
	v_cmp_ge_f32_e32 vcc, s88, v121
	s_cmp_eq_u64 vcc, exec
	v_mfma_f32_32x32x16_bf16 v[0:15], v[124:127], v[184:187], v[0:15]
	v_mfma_f32_32x32x16_bf16 v[0:15], v[172:175], v[188:191], v[0:15]
	v_mfma_f32_32x32x16_bf16 v[0:15], v[168:171], v[192:195], v[0:15]
	s_cbranch_scc1 .LBB0_742
	s_branch .Li0_rare
	s_mov_b64 s[54:55], 0xe404000
	v_lshl_add_u64 v[64:65], v[134:135], 0, s[54:55]
	s_add_i32 m0, s96, 0x8000
	s_mov_b64 s[54:55], 0xe406000
	global_load_lds_dwordx4 v[64:65], off
	v_lshl_add_u64 v[64:65], v[134:135], 0, s[54:55]
	s_add_i32 m0, s96, 0xa000
	s_mov_b64 s[54:55], 0xe804000
	global_load_lds_dwordx4 v[64:65], off
	v_lshl_add_u64 v[64:65], v[134:135], 0, s[54:55]
	s_add_i32 m0, s96, 0xc000
	s_mov_b64 s[54:55], 0xe806000
	global_load_lds_dwordx4 v[64:65], off
	v_lshl_add_u64 v[64:65], v[134:135], 0, s[54:55]
	s_add_i32 m0, s96, 0xe000
	s_cmp_gt_i32 s19, s18
	global_load_lds_dwordx4 v[64:65], off
	s_cbranch_scc1 .LBB0_737
	v_lshl_add_u64 v[64:65], s[50:51], 0, v[130:131]
	s_mov_b64 s[54:55], 0xc40a000
	v_lshl_add_u64 v[66:67], v[64:65], 0, s[54:55]
	s_mov_b64 s[54:55], 0xc408000
	s_mov_b32 m0, s97
	v_lshl_add_u64 v[64:65], v[64:65], 0, s[54:55]
	global_load_lds_dwordx4 v[64:65], off
	s_mov_b32 m0, s26
	s_nop 0
	global_load_lds_dwordx4 v[66:67], off

.Li1_entry:
	ds_read_b128 v[64:67], v148
	ds_read_b128 v[188:191], v150
	ds_read_b128 v[228:231], v152
	s_waitcnt lgkmcnt(2)
	v_mfma_f32_32x32x16_bf16 v[64:79], v[64:67], v[80:83], 0
	s_waitcnt lgkmcnt(1)
	v_mfma_f32_32x32x16_bf16 v[64:79], v[188:191], v[84:87], v[64:79]
	ds_read_b128 v[188:191], v154
	s_mov_b64 s[56:57], 0xe408000
	s_mov_b32 m0, s96
	v_lshl_add_u64 v[192:193], v[134:135], 0, s[56:57]
	s_nop 0
	global_load_lds_dwordx4 v[192:193], off
	v_cndmask_b32_e64 v173, v113, v121, s[2:3]
	v_cndmask_b32_e64 v172, v112, v120, s[2:3]
	v_cndmask_b32_e64 v177, v121, v113, s[2:3]
	v_cndmask_b32_e64 v176, v120, v112, s[2:3]
	s_waitcnt lgkmcnt(1)
	v_mfma_f32_32x32x16_bf16 v[64:79], v[228:231], v[88:91], v[64:79]
	ds_read_b128 v[228:231], v148 offset:128
	s_mov_b64 s[56:57], 0xe40a000
	s_mov_b32 m0, s6
	v_lshl_add_u64 v[192:193], v[134:135], 0, s[56:57]
	s_nop 0
	global_load_lds_dwordx4 v[192:193], off
	v_cndmask_b32_e64 v171, v127, v119, s[2:3]
	v_cndmask_b32_e64 v170, v126, v118, s[2:3]
	v_cndmask_b32_e64 v169, v125, v117, s[2:3]
	v_cndmask_b32_e64 v168, v124, v116, s[2:3]
	s_waitcnt lgkmcnt(1)
	v_mfma_f32_32x32x16_bf16 v[64:79], v[188:191], v[92:95], v[64:79]
	ds_read_b128 v[188:191], v150 offset:128
	s_mov_b64 s[56:57], 0xe808000
	s_mov_b32 m0, s7
	v_lshl_add_u64 v[192:193], v[134:135], 0, s[56:57]
	s_nop 0
	global_load_lds_dwordx4 v[192:193], off
	v_cndmask_b32_e64 v175, v115, v123, s[2:3]
	v_cndmask_b32_e64 v174, v114, v122, s[2:3]
	v_cndmask_b32_e64 v127, v119, v127, s[2:3]
	v_cndmask_b32_e64 v126, v118, v126, s[2:3]
	s_waitcnt lgkmcnt(1)
	v_mfma_f32_32x32x16_bf16 v[64:79], v[228:231], v[96:99], v[64:79]
	ds_read_b128 v[228:231], v152 offset:128
	s_mov_b64 s[56:57], 0xe80a000
	s_mov_b32 m0, s24
	v_lshl_add_u64 v[192:193], v[134:135], 0, s[56:57]
	s_nop 0
	global_load_lds_dwordx4 v[192:193], off
	v_cndmask_b32_e64 v125, v117, v125, s[2:3]
	v_cndmask_b32_e64 v124, v116, v124, s[2:3]
	v_cndmask_b32_e64 v179, v123, v115, s[2:3]
	v_cndmask_b32_e64 v178, v122, v114, s[2:3]
	s_waitcnt lgkmcnt(1)
	v_mfma_f32_32x32x16_bf16 v[64:79], v[188:191], v[100:103], v[64:79]
	ds_read_b128 v[188:191], v154 offset:128
	s_add_i32 s56, s19, 1
	s_cmp_gt_i32 s56, s18
	s_cbranch_scc1 .Li1_kskip
	v_lshl_add_u64 v[192:193], s[50:51], 0, v[130:131]
	s_mov_b64 s[56:57], 0xc40c000
	s_mov_b32 m0, s27
	v_lshl_add_u64 v[192:193], v[192:193], 0, s[56:57]
	s_nop 0
	global_load_lds_dwordx4 v[192:193], off
	v_lshl_add_u64 v[192:193], s[50:51], 0, v[130:131]
	s_mov_b64 s[56:57], 0xc40e000
	s_mov_b32 m0, s62
	v_lshl_add_u64 v[192:193], v[192:193], 0, s[56:57]
	s_nop 0
	global_load_lds_dwordx4 v[192:193], off
.Li1_kskip:
	ds_read_b64_tr_b16 v[180:181], v158 offset:0x8000
	ds_read_b64_tr_b16 v[182:183], v158 offset:0x8800
	ds_read_b64_tr_b16 v[184:185], v158 offset:0x9000
	ds_read_b64_tr_b16 v[186:187], v158 offset:0x9800
	s_waitcnt lgkmcnt(5)
	v_mfma_f32_32x32x16_bf16 v[64:79], v[228:231], v[104:107], v[64:79]
	v_max_f32_e32 v194, v128, v128
	v_max_f32_e32 v195, v164, v164
	v_max_f32_e32 v194, v195, v194
	v_sub_f32_e32 v195, v194, v166
	v_mul_f32_e32 v195, 0x3db504f3, v195
	v_cmp_ge_f32_e32 vcc, s88, v195
	s_waitcnt lgkmcnt(4)
	v_mfma_f32_32x32x16_bf16 v[64:79], v[188:191], v[108:111], v[64:79]
	s_cmp_eq_u64 vcc, exec
	s_cbranch_scc0 .Li1_fb
	v_mov_b32_e32 v165, v166
	s_cmp_le_i32 s83, s25
	s_cbranch_scc1 .Li1_sm
	s_nop 7
	v_add_u32_e32 v112, 27, v162
	v_cmp_gt_u32_e32 vcc, s86, v112
	v_add_u32_e32 v112, s83, v163
	v_subrev_u32_e32 v112, 31, v112
	v_cndmask_b32_e32 v64, v141, v64, vcc
	v_cmp_lt_u32_e32 vcc, s87, v112
	v_add_u32_e32 v112, 25, v162
	s_nop 0
	v_cndmask_b32_e32 v65, v141, v65, vcc
	v_cmp_gt_u32_e32 vcc, s86, v112
	v_add_u32_e32 v112, 24, v162
	s_nop 0
	v_cndmask_b32_e32 v66, v141, v66, vcc
	v_cmp_gt_u32_e32 vcc, s86, v112
	v_add_u32_e32 v112, 19, v162
	s_nop 0
	v_cndmask_b32_e32 v67, v141, v67, vcc
	v_cmp_gt_u32_e32 vcc, s86, v112
	v_add_u32_e32 v112, 18, v162
	s_nop 0
	v_cndmask_b32_e32 v68, v141, v68, vcc
	v_cmp_gt_u32_e32 vcc, s86, v112
	v_add_u32_e32 v112, 17, v162
	s_nop 0
	v_cndmask_b32_e32 v69, v141, v69, vcc
	v_cmp_gt_u32_e32 vcc, s86, v112
	v_add_u32_e32 v112, 16, v162
	s_nop 0
	v_cndmask_b32_e32 v70, v141, v70, vcc
	v_cmp_gt_u32_e32 vcc, s86, v112
	v_add_u32_e32 v112, 11, v162
	s_nop 0
	v_cndmask_b32_e32 v71, v141, v71, vcc
	v_cmp_gt_u32_e32 vcc, s86, v112
	v_add_u32_e32 v112, 10, v162
	s_nop 0
	v_cndmask_b32_e32 v72, v141, v72, vcc
	v_cmp_gt_u32_e32 vcc, s86, v112
	v_add_u32_e32 v112, 9, v162
	s_nop 0
	v_cndmask_b32_e32 v73, v141, v73, vcc
	v_cmp_gt_u32_e32 vcc, s86, v112
	v_add_u32_e32 v112, 8, v162
	s_nop 0
	v_cndmask_b32_e32 v74, v141, v74, vcc
	v_cmp_gt_u32_e32 vcc, s86, v112
	v_add_u32_e32 v112, 3, v162
	s_nop 0
	v_cndmask_b32_e32 v75, v141, v75, vcc
	v_cmp_gt_u32_e32 vcc, s86, v112
	v_add_u32_e32 v112, 2, v162
	s_nop 0
	v_cndmask_b32_e32 v76, v141, v76, vcc
	v_cmp_gt_u32_e32 vcc, s86, v112
	v_add_u32_e32 v112, 1, v162
	s_nop 0
	v_cndmask_b32_e32 v77, v141, v77, vcc
	v_cmp_gt_u32_e32 vcc, s86, v112
	s_nop 1
	v_cndmask_b32_e32 v78, v141, v78, vcc
	v_cmp_gt_u32_e32 vcc, s86, v162
	s_nop 1
	v_cndmask_b32_e32 v79, v141, v79, vcc
.Li1_sm:
	ds_read_b64_tr_b16 v[188:189], v158 offset:0xa000
	ds_read_b64_tr_b16 v[190:191], v158 offset:0xa800
	ds_read_b64_tr_b16 v[192:193], v158 offset:0xb000
	ds_read_b64_tr_b16 v[194:195], v158 offset:0xb800
	s_waitcnt lgkmcnt(4)
	s_nop 1
	v_mfma_f32_32x32x16_bf16 v[48:63], v[176:179], v[180:183], v[48:63]
	ds_read_b64_tr_b16 v[180:181], v158 offset:0x8200
	ds_read_b64_tr_b16 v[182:183], v158 offset:0x8a00
	v_mul_f32_e32 v114, 0xbe0293ee, v165
	v_max_f32_e32 v112, v65, v65
	v_max_f32_e32 v113, v64, v64
	v_fmamk_f32 v64, v64, 0x3e0293ee, v114
	v_max_f32_e32 v112, v113, v112
	v_exp_f32_e32 v64, v64
	v_mfma_f32_32x32x16_bf16 v[48:63], v[168:171], v[184:187], v[48:63]
	ds_read_b64_tr_b16 v[184:185], v158 offset:0x9200
	ds_read_b64_tr_b16 v[186:187], v158 offset:0x9a00
	v_fmamk_f32 v65, v65, 0x3e0293ee, v114
	v_max3_f32 v112, v112, v66, v67
	v_exp_f32_e32 v65, v65
	v_fmamk_f32 v66, v66, 0x3e0293ee, v114
	v_exp_f32_e32 v66, v66
	v_fmamk_f32 v67, v67, 0x3e0293ee, v114
	s_waitcnt lgkmcnt(6)
	v_mfma_f32_32x32x16_bf16 v[48:63], v[172:175], v[188:191], v[48:63]
	ds_read_b64_tr_b16 v[188:189], v158 offset:0xa200
	ds_read_b64_tr_b16 v[190:191], v158 offset:0xaa00
	v_max3_f32 v112, v112, v68, v69
	v_exp_f32_e32 v67, v67
	v_fmamk_f32 v68, v68, 0x3e0293ee, v114
	v_add_f32_e32 v115, 0, v64
	v_exp_f32_e32 v68, v68
	v_fmamk_f32 v69, v69, 0x3e0293ee, v114
	s_waitcnt lgkmcnt(6)
	v_mfma_f32_32x32x16_bf16 v[48:63], v[124:127], v[192:195], v[48:63]
	ds_read_b64_tr_b16 v[192:193], v158 offset:0xb200
	ds_read_b64_tr_b16 v[194:195], v158 offset:0xba00
	v_max3_f32 v112, v112, v70, v71
	v_add_f32_e32 v115, v65, v115
	v_exp_f32_e32 v69, v69
	v_fmamk_f32 v70, v70, 0x3e0293ee, v114
	v_add_f32_e32 v115, v66, v115
	v_exp_f32_e32 v70, v70
	s_waitcnt lgkmcnt(0)
	v_mfma_f32_32x32x16_bf16 v[32:47], v[176:179], v[180:183], v[32:47]
	ds_read_b64_tr_b16 v[180:181], v158 offset:0x8400
	ds_read_b64_tr_b16 v[182:183], v158 offset:0x8c00
	v_fmamk_f32 v71, v71, 0x3e0293ee, v114
	v_max3_f32 v112, v112, v72, v73
	v_add_f32_e32 v115, v67, v115
	v_exp_f32_e32 v71, v71
	v_fmamk_f32 v72, v72, 0x3e0293ee, v114
	v_add_f32_e32 v115, v68, v115
	v_mfma_f32_32x32x16_bf16 v[32:47], v[168:171], v[184:187], v[32:47]
	ds_read_b64_tr_b16 v[184:185], v158 offset:0x9400
	ds_read_b64_tr_b16 v[186:187], v158 offset:0x9c00
	v_exp_f32_e32 v72, v72
	v_fmamk_f32 v73, v73, 0x3e0293ee, v114
	v_max3_f32 v112, v112, v74, v75
	v_add_f32_e32 v115, v69, v115
	v_exp_f32_e32 v73, v73
	v_fmamk_f32 v74, v74, 0x3e0293ee, v114
	v_mfma_f32_32x32x16_bf16 v[32:47], v[172:175], v[188:191], v[32:47]
	ds_read_b64_tr_b16 v[188:189], v158 offset:0xa400
	ds_read_b64_tr_b16 v[190:191], v158 offset:0xac00
	v_add_f32_e32 v115, v70, v115
	v_exp_f32_e32 v74, v74
	v_fmamk_f32 v75, v75, 0x3e0293ee, v114
	v_max3_f32 v112, v112, v76, v77
	v_add_f32_e32 v115, v71, v115
	v_exp_f32_e32 v75, v75
	v_mfma_f32_32x32x16_bf16 v[32:47], v[124:127], v[192:195], v[32:47]
	ds_read_b64_tr_b16 v[192:193], v158 offset:0xb400
	ds_read_b64_tr_b16 v[194:195], v158 offset:0xbc00
	v_fmamk_f32 v76, v76, 0x3e0293ee, v114
	v_add_f32_e32 v115, v72, v115
	v_exp_f32_e32 v76, v76
	v_fmamk_f32 v77, v77, 0x3e0293ee, v114
	v_max3_f32 v112, v112, v78, v79
	v_add_f32_e32 v115, v73, v115
	s_waitcnt lgkmcnt(0)
	v_mfma_f32_32x32x16_bf16 v[16:31], v[176:179], v[180:183], v[16:31]
	ds_read_b64_tr_b16 v[180:181], v158 offset:0x8600
	ds_read_b64_tr_b16 v[182:183], v158 offset:0x8e00
	v_exp_f32_e32 v77, v77
	v_fmamk_f32 v78, v78, 0x3e0293ee, v114
	v_add_f32_e32 v115, v74, v115
	v_exp_f32_e32 v78, v78
	v_fmac_f32_e32 v114, 0x3e0293ee, v79
	v_add_f32_e32 v115, v75, v115
	v_mfma_f32_32x32x16_bf16 v[16:31], v[168:171], v[184:187], v[16:31]
	ds_read_b64_tr_b16 v[184:185], v158 offset:0x9600
	ds_read_b64_tr_b16 v[186:187], v158 offset:0x9e00
	v_exp_f32_e32 v79, v114
	v_add_f32_e32 v114, v76, v115
	v_mov_b32_e32 v113, v112
	v_add_f32_e32 v114, v77, v114
	s_nop 0
	v_permlane32_swap_b32_e32 v112, v113
	v_add_f32_e32 v114, v78, v114
	v_mfma_f32_32x32x16_bf16 v[16:31], v[172:175], v[188:191], v[16:31]
	ds_read_b64_tr_b16 v[188:189], v158 offset:0xa600
	ds_read_b64_tr_b16 v[190:191], v158 offset:0xae00
	v_add_f32_e32 v120, v79, v114
	v_max_f32_e32 v113, v113, v113
	v_max_f32_e32 v112, v112, v112
	v_max_f32_e32 v164, v112, v113
	v_mov_b32_e32 v121, v120
	v_cvt_pk_bf16_f32 v112, v64, v65
	v_mfma_f32_32x32x16_bf16 v[16:31], v[124:127], v[192:195], v[16:31]
	ds_read_b64_tr_b16 v[192:193], v158 offset:0xb600
	ds_read_b64_tr_b16 v[194:195], v158 offset:0xbe00
	v_cvt_pk_bf16_f32 v113, v66, v67
	v_cvt_pk_bf16_f32 v114, v68, v69
	v_cvt_pk_bf16_f32 v115, v70, v71
	v_cvt_pk_bf16_f32 v116, v72, v73
	v_cvt_pk_bf16_f32 v117, v74, v75
	v_cvt_pk_bf16_f32 v118, v76, v77
	s_waitcnt lgkmcnt(0)
	v_mfma_f32_32x32x16_bf16 v[0:15], v[176:179], v[180:183], v[0:15]
	v_cvt_pk_bf16_f32 v119, v78, v79
	s_nop 1
	v_permlane32_swap_b32_e32 v120, v121
	v_permlane32_swap_b32_e32 v112, v114
	v_permlane32_swap_b32_e32 v113, v115
	v_permlane32_swap_b32_e32 v116, v118
	v_permlane32_swap_b32_e32 v117, v119
	v_mfma_f32_32x32x16_bf16 v[0:15], v[168:171], v[184:187], v[0:15]
	ds_write_b128 v157, v[112:115]
	ds_write_b128 v157, v[116:119] offset:1024
	v_add_f32_e32 v120, v120, v121
	v_add_f32_e32 v155, v155, v120
	v_mfma_f32_32x32x16_bf16 v[0:15], v[172:175], v[188:191], v[0:15]
	v_mfma_f32_32x32x16_bf16 v[0:15], v[124:127], v[192:195], v[0:15]
	s_and_saveexec_b64 s[54:55], s[4:5]
	ds_write_b32 v160, v164 offset:8192
	s_or_b64 exec, exec, s[54:55]
	s_waitcnt vmcnt(0)
	s_waitcnt vmcnt(0) lgkmcnt(0)
	s_barrier
	s_branch .LBB0_733
.Li1_fb:
	ds_read_b64_tr_b16 v[180:181], v158 offset:0x8000
	ds_read_b64_tr_b16 v[182:183], v158 offset:0x8800
	ds_read_b64_tr_b16 v[184:185], v158 offset:0x9000
	ds_read_b64_tr_b16 v[186:187], v158 offset:0x9800
	ds_read_b64_tr_b16 v[188:189], v158 offset:0xa000
	ds_read_b64_tr_b16 v[190:191], v158 offset:0xa800
	ds_read_b64_tr_b16 v[192:193], v158 offset:0xb000
	ds_read_b64_tr_b16 v[194:195], v158 offset:0xb800
	s_waitcnt lgkmcnt(0)
	s_waitcnt lgkmcnt(0)
	v_max_f32_e32 v120, v128, v128
	v_max_f32_e32 v121, v164, v164
	v_max_f32_e32 v120, v121, v120
	s_nop 1
	v_mfma_f32_32x32x16_bf16 v[48:63], v[176:179], v[180:183], v[48:63]
	ds_read_b64_tr_b16 v[180:181], v158 offset:0x8200
	ds_read_b64_tr_b16 v[182:183], v158 offset:0x8a00
	v_mfma_f32_32x32x16_bf16 v[48:63], v[168:171], v[184:187], v[48:63]
	ds_read_b64_tr_b16 v[184:185], v158 offset:0x9200
	ds_read_b64_tr_b16 v[186:187], v158 offset:0x9a00
	v_mfma_f32_32x32x16_bf16 v[48:63], v[172:175], v[188:191], v[48:63]
	ds_read_b64_tr_b16 v[188:189], v158 offset:0xa200
	ds_read_b64_tr_b16 v[190:191], v158 offset:0xaa00
	v_mfma_f32_32x32x16_bf16 v[48:63], v[124:127], v[192:195], v[48:63]
	ds_read_b64_tr_b16 v[192:193], v158 offset:0xb200
	ds_read_b64_tr_b16 v[194:195], v158 offset:0xba00
	s_waitcnt lgkmcnt(0)
	v_mfma_f32_32x32x16_bf16 v[32:47], v[176:179], v[180:183], v[32:47]
	ds_read_b64_tr_b16 v[180:181], v158 offset:0x8400
	ds_read_b64_tr_b16 v[182:183], v158 offset:0x8c00
	v_mfma_f32_32x32x16_bf16 v[32:47], v[168:171], v[184:187], v[32:47]
	ds_read_b64_tr_b16 v[184:185], v158 offset:0x9400
	ds_read_b64_tr_b16 v[186:187], v158 offset:0x9c00
	v_mfma_f32_32x32x16_bf16 v[32:47], v[172:175], v[188:191], v[32:47]
	ds_read_b64_tr_b16 v[188:189], v158 offset:0xa400
	ds_read_b64_tr_b16 v[190:191], v158 offset:0xac00
	v_mfma_f32_32x32x16_bf16 v[32:47], v[124:127], v[192:195], v[32:47]
	ds_read_b64_tr_b16 v[192:193], v158 offset:0xb400
	ds_read_b64_tr_b16 v[194:195], v158 offset:0xbc00
	s_waitcnt lgkmcnt(0)
	v_mfma_f32_32x32x16_bf16 v[16:31], v[176:179], v[180:183], v[16:31]
	ds_read_b64_tr_b16 v[180:181], v158 offset:0x8600
	ds_read_b64_tr_b16 v[182:183], v158 offset:0x8e00
	v_mfma_f32_32x32x16_bf16 v[16:31], v[168:171], v[184:187], v[16:31]
	ds_read_b64_tr_b16 v[184:185], v158 offset:0x9600
	ds_read_b64_tr_b16 v[186:187], v158 offset:0x9e00
	v_mfma_f32_32x32x16_bf16 v[16:31], v[172:175], v[188:191], v[16:31]
	ds_read_b64_tr_b16 v[188:189], v158 offset:0xa600
	ds_read_b64_tr_b16 v[190:191], v158 offset:0xae00
	v_mfma_f32_32x32x16_bf16 v[16:31], v[124:127], v[192:195], v[16:31]
	ds_read_b64_tr_b16 v[192:193], v158 offset:0xb600
	ds_read_b64_tr_b16 v[194:195], v158 offset:0xbe00
	s_waitcnt lgkmcnt(0)
	v_mfma_f32_32x32x16_bf16 v[0:15], v[176:179], v[180:183], v[0:15]
	v_sub_f32_e32 v121, v120, v166
	v_mul_f32_e32 v121, 0x3db504f3, v121
	v_cmp_ge_f32_e32 vcc, s88, v121
	s_cmp_eq_u64 vcc, exec
	v_mfma_f32_32x32x16_bf16 v[0:15], v[168:171], v[184:187], v[0:15]
	v_mfma_f32_32x32x16_bf16 v[0:15], v[172:175], v[188:191], v[0:15]
	v_mfma_f32_32x32x16_bf16 v[0:15], v[124:127], v[192:195], v[0:15]
	s_cbranch_scc1 .LBB0_756
	s_branch .Li1_rare
	s_mov_b64 s[56:57], 0xe408000
	s_mov_b32 m0, s96
	v_lshl_add_u64 v[64:65], v[134:135], 0, s[56:57]
	s_mov_b64 s[56:57], 0xe40a000
	global_load_lds_dwordx4 v[64:65], off
	v_lshl_add_u64 v[64:65], v[134:135], 0, s[56:57]
	s_mov_b32 m0, s6
	s_mov_b64 s[56:57], 0xe808000
	global_load_lds_dwordx4 v[64:65], off
	v_lshl_add_u64 v[64:65], v[134:135], 0, s[56:57]
	s_mov_b32 m0, s7
	s_mov_b64 s[56:57], 0xe80a000
	global_load_lds_dwordx4 v[64:65], off
	v_lshl_add_u64 v[64:65], v[134:135], 0, s[56:57]
	s_mov_b32 m0, s24
	s_add_i32 s56, s19, 1
	global_load_lds_dwordx4 v[64:65], off
	s_cmp_gt_i32 s56, s18
	s_cbranch_scc1 .LBB0_751
	v_lshl_add_u64 v[64:65], s[50:51], 0, v[130:131]
	s_mov_b64 s[56:57], 0xc40e000
	v_lshl_add_u64 v[66:67], v[64:65], 0, s[56:57]
	s_mov_b64 s[56:57], 0xc40c000
	s_mov_b32 m0, s27
	v_lshl_add_u64 v[64:65], v[64:65], 0, s[56:57]
	global_load_lds_dwordx4 v[64:65], off
	s_mov_b32 m0, s62
	s_nop 0
	global_load_lds_dwordx4 v[66:67], off
